# RG-LRU item prologue: 64 gate-weight loads issued together (one wait) instead of 32 serialized round trips; on v063
# baseline (speedup 1.0000x reference)
; __device__ __forceinline__ unsigned pk2(float lo, float hi) { unsigned r; asm("v_cvt_pk_bf16_f32 %0, %1, %2" : "=v"(r) : "v"(lo), "v"(hi)); return r; }
; #define FIN(k) ((const float*)ptab(F.tab, (k)))
; __device__ __forceinline__ void lru_item(Frame& F, int l, int item) {
;     ...
;         const int cch = g * 64 + lane;
;         const float* conv_w = FIN(I_CONVW);
;         const float cw0 = conv_w[(l * 4 + 0) * RW + cch], cw1 = conv_w[(l * 4 + 1) * RW + cch], cw2 = conv_w[(l * 4 + 2) * RW + cch], cw3 = conv_w[(l * 4 + 3) * RW + cch], cb = FIN(I_CONVB)[l * RW + cch];
;         bf16x8 Bf[2][2][2];
; #pragma unroll
;         for (int gate = 0; gate < 2; ++gate) { const float* W = (gate ? FIN(I_WGX) : FIN(I_WGA)) + (size_t)(l * 8 + g) * 64 * 64;
; #pragma unroll
;             for (int n = 0; n < 2; ++n)
; #pragma unroll
;                 for (int kk = 0; kk < 2; ++kk) { const float* wp = W + (size_t)(32 * kk + 8 * q) * 64 + hf * 32 + 16 * n + r; v4u pw;
;                     pw.x = pk2(wp[0 * 64], wp[1 * 64]); pw.y = pk2(wp[2 * 64], wp[3 * 64]); pw.z = pk2(wp[4 * 64], wp[5 * 64]); pw.w = pk2(wp[6 * 64], wp[7 * 64]);
;                     Bf[gate][n][kk] = __builtin_bit_cast(bf16x8, pw); } }
.LBB0_464:
	s_ashr_i32 s10, s2, 4
	v_readfirstlane_b32 s27, v0
	v_mov_b32_e32 v0, s34
	s_ashr_i32 s11, s10, 31
	s_mul_i32 s8, s10, 0xa00000
	v_and_b32_e32 v32, 63, v2
	v_and_b32_e32 v44, 15, v2
	v_bfe_u32 v33, v2, 4, 2
	v_readfirstlane_b32 s26, v1
	ds_read2_b64 v[0:3], v0 offset1:1
	s_mul_hi_i32 s9, s10, 0xa00000
	s_add_u32 s8, s0, s8
	s_addc_u32 s9, s1, s9
	s_bfe_u32 s0, s2, 0x30001
	s_lshl_b32 s25, s0, 6
	s_lshl_b32 s1, s2, 5
	v_or_b32_e32 v36, s25, v32
	s_and_b32 s24, s1, 32
	s_waitcnt lgkmcnt(0)
	v_readfirstlane_b32 s1, v1
	v_readfirstlane_b32 s13, v0
	v_or_b32_e32 v4, s18, v36
	v_mov_b32_e32 v1, s1
	v_mov_b32_e32 v0, s13
	v_ashrrev_i32_e32 v5, 31, v4
	v_lshl_add_u64 v[0:1], v[4:5], 2, v[0:1]
	s_movk_i32 s1, 0x1000
	global_load_dword v45, v[0:1], off
	global_load_dword v46, v[0:1], off offset:2048
	v_add_co_u32_e32 v0, vcc, s1, v0
	v_readfirstlane_b32 s1, v3
	s_nop 0
	v_addc_co_u32_e32 v1, vcc, 0, v1, vcc
	v_readfirstlane_b32 s13, v2
	v_or_b32_e32 v2, s19, v36
	global_load_dword v47, v[0:1], off
	global_load_dword v48, v[0:1], off offset:2048
	v_mov_b32_e32 v0, s13
	v_mov_b32_e32 v1, s1
	v_ashrrev_i32_e32 v3, 31, v2
	v_lshl_add_u64 v[0:1], v[2:3], 2, v[0:1]
	global_load_dword v49, v[0:1], off
	v_mov_b32_e32 v0, s35
	ds_read_b64 v[0:1], v0
	s_or_b32 s0, s0, s20
	s_ashr_i32 s1, s0, 31
	s_ashr_i32 s12, s3, 6
	s_lshl_b64 s[0:1], s[0:1], 14
	s_waitcnt lgkmcnt(0)
	v_readfirstlane_b32 s14, v0
	v_readfirstlane_b32 s13, v1
	s_add_u32 s14, s14, s0
	s_addc_u32 s13, s13, s1
	s_lshl_b32 s16, s24, 2
	s_add_u32 s14, s14, s16
	s_addc_u32 s15, s13, 0
	v_lshlrev_b32_e32 v194, 2, v44
	v_lshl_add_u64 v[4:5], s[14:15], 0, v[194:195]
	v_lshlrev_b32_e32 v16, 11, v33
	v_mov_b32_e32 v17, v195
	v_lshl_add_u64 v[12:13], v[4:5], 0, v[16:17]
	global_load_dword v128, v[12:13], off
	global_load_dword v129, v[12:13], off offset:256
	v_or_b32_e32 v20, 0x2000, v16
	v_mov_b32_e32 v21, v195
	v_lshl_add_u64 v[18:19], v[4:5], 0, v[20:21]
	v_mov_b32_e32 v58, 0
	v_mov_b32_e32 v59, 0
	v_mov_b32_e32 v60, 0
	global_load_dword v130, v[12:13], off offset:512
	global_load_dword v131, v[12:13], off offset:768
	global_load_dword v132, v[12:13], off offset:1024
	global_load_dword v133, v[12:13], off offset:1280
	global_load_dword v134, v[12:13], off offset:1536
	global_load_dword v135, v[12:13], off offset:1792
	global_load_dword v136, v[18:19], off
	global_load_dword v137, v[18:19], off offset:256
	global_load_dword v138, v[18:19], off offset:512
	global_load_dword v139, v[18:19], off offset:768
	global_load_dword v140, v[18:19], off offset:1024
	global_load_dword v141, v[18:19], off offset:1280
	global_load_dword v142, v[18:19], off offset:1536
	global_load_dword v143, v[18:19], off offset:1792
	global_load_dword v144, v[12:13], off offset:64
	global_load_dword v145, v[12:13], off offset:320
	global_load_dword v146, v[12:13], off offset:576
	global_load_dword v147, v[12:13], off offset:832
	global_load_dword v148, v[12:13], off offset:1088
	global_load_dword v149, v[12:13], off offset:1344
	global_load_dword v150, v[12:13], off offset:1600
	s_nop 0
	global_load_dword v151, v[12:13], off offset:1856
	global_load_dword v152, v[18:19], off offset:64
	global_load_dword v153, v[18:19], off offset:320
	global_load_dword v154, v[18:19], off offset:576
	global_load_dword v155, v[18:19], off offset:832
	global_load_dword v156, v[18:19], off offset:1088
	global_load_dword v157, v[18:19], off offset:1344
	global_load_dword v158, v[18:19], off offset:1600
	s_nop 0
	global_load_dword v159, v[18:19], off offset:1856
	v_mov_b32_e32 v18, s36
	ds_read_b64 v[18:19], v18
	s_waitcnt lgkmcnt(0)
; __device__ __forceinline__ unsigned pk2(float lo, float hi) { unsigned r; asm("v_cvt_pk_bf16_f32 %0, %1, %2" : "=v"(r) : "v"(lo), "v"(hi)); return r; }
; __device__ __forceinline__ float bf2f(unsigned short v) { return __uint_as_float((unsigned)v << 16); }
; #define FIN(k) ((const float*)ptab(F.tab, (k)))
; __device__ __forceinline__ void lru_item(Frame& F, int l, int item) {
;     ...
;         bf16x8 Bf[2][2][2];
; #pragma unroll
;         for (int gate = 0; gate < 2; ++gate) { const float* W = (gate ? FIN(I_WGX) : FIN(I_WGA)) + (size_t)(l * 8 + g) * 64 * 64;
; #pragma unroll
;             for (int n = 0; n < 2; ++n)
; #pragma unroll
;                 for (int kk = 0; kk < 2; ++kk) { const float* wp = W + (size_t)(32 * kk + 8 * q) * 64 + hf * 32 + 16 * n + r; v4u pw;
;                     pw.x = pk2(wp[0 * 64], wp[1 * 64]); pw.y = pk2(wp[2 * 64], wp[3 * 64]); pw.z = pk2(wp[4 * 64], wp[5 * 64]); pw.w = pk2(wp[6 * 64], wp[7 * 64]);
;                     Bf[gate][n][kk] = __builtin_bit_cast(bf16x8, pw); } }
;         float ba[2], bx[2], sp8[2];
; #pragma unroll
;         for (int n = 0; n < 2; ++n) { const int ch = l * RW + g * 64 + hf * 32 + 16 * n + r; ba[n] = FIN(I_BGA)[ch]; bx[n] = FIN(I_BGX)[ch];
;             const float z = -FIN(I_LRULAM)[ch]; sp8[n] = 8.f * (fmaxf(z, 0.f) + log1pf(__expf(-fabsf(z)))); }
;         const bf16* xcol = pj + 3 * AW + cch;
;         float h3 = 0.f, h2 = 0.f, h1 = 0.f;
;         if (t0 != 0) { h3 = bf2f(xcol[(size_t)(t0 - 3) * INW]); h2 = bf2f(xcol[(size_t)(t0 - 2) * INW]); h1 = bf2f(xcol[(size_t)(t0 - 1) * INW]); }
	v_readfirstlane_b32 s14, v18
	v_readfirstlane_b32 s13, v19
	s_add_u32 s0, s14, s0
	s_addc_u32 s1, s13, s1
	s_add_u32 s0, s0, s16
	s_addc_u32 s1, s1, 0
	v_lshl_add_u64 v[22:23], s[0:1], 0, v[194:195]
	v_lshl_add_u64 v[28:29], v[22:23], 0, v[16:17]
	global_load_dword v160, v[28:29], off
	global_load_dword v161, v[28:29], off offset:256
	v_lshl_add_u64 v[34:35], v[22:23], 0, v[20:21]
	s_or_b32 s0, s24, s19
	s_or_b32 s0, s0, s25
	s_lshl_b32 s23, s12, 8
	v_lshlrev_b32_e32 v194, 1, v36
	v_lshl_add_u64 v[36:37], s[8:9], 0, v[194:195]
	s_cmp_lt_u32 s3, 64
	global_load_dword v162, v[28:29], off offset:512
	global_load_dword v163, v[28:29], off offset:768
	global_load_dword v164, v[28:29], off offset:1024
	global_load_dword v165, v[28:29], off offset:1280
	global_load_dword v166, v[28:29], off offset:1536
	global_load_dword v167, v[28:29], off offset:1792
	global_load_dword v168, v[34:35], off
	global_load_dword v169, v[34:35], off offset:256
	global_load_dword v170, v[34:35], off offset:512
	global_load_dword v171, v[34:35], off offset:768
	global_load_dword v172, v[34:35], off offset:1024
	global_load_dword v173, v[34:35], off offset:1280
	global_load_dword v174, v[34:35], off offset:1536
	global_load_dword v175, v[34:35], off offset:1792
	global_load_dword v176, v[28:29], off offset:64
	global_load_dword v177, v[28:29], off offset:320
	global_load_dword v178, v[28:29], off offset:576
	global_load_dword v179, v[28:29], off offset:832
	global_load_dword v180, v[28:29], off offset:1088
	global_load_dword v181, v[28:29], off offset:1344
	global_load_dword v182, v[28:29], off offset:1600
	s_nop 0
	global_load_dword v183, v[28:29], off offset:1856
	global_load_dword v184, v[34:35], off offset:64
	global_load_dword v185, v[34:35], off offset:320
	global_load_dword v186, v[34:35], off offset:576
	global_load_dword v187, v[34:35], off offset:832
	global_load_dword v188, v[34:35], off offset:1088
	global_load_dword v189, v[34:35], off offset:1344
	global_load_dword v190, v[34:35], off offset:1600
	s_nop 0
	global_load_dword v191, v[34:35], off offset:1856
	v_mov_b32_e32 v35, s37
	ds_read_b64 v[42:43], v35
	v_mov_b32_e32 v35, s44
	ds_read_b128 v[38:41], v35
	s_waitcnt vmcnt(0)
	v_cvt_pk_bf16_f32 v0, v128, v129
	v_cvt_pk_bf16_f32 v1, v130, v131
	v_cvt_pk_bf16_f32 v2, v132, v133
	v_cvt_pk_bf16_f32 v3, v134, v135
	v_cvt_pk_bf16_f32 v4, v136, v137
	v_cvt_pk_bf16_f32 v5, v138, v139
	v_cvt_pk_bf16_f32 v6, v140, v141
	v_cvt_pk_bf16_f32 v7, v142, v143
	v_cvt_pk_bf16_f32 v8, v144, v145
	v_cvt_pk_bf16_f32 v9, v146, v147
	v_cvt_pk_bf16_f32 v10, v148, v149
	v_cvt_pk_bf16_f32 v11, v150, v151
	v_cvt_pk_bf16_f32 v12, v152, v153
	v_cvt_pk_bf16_f32 v13, v154, v155
	v_cvt_pk_bf16_f32 v14, v156, v157
	v_cvt_pk_bf16_f32 v15, v158, v159
	v_cvt_pk_bf16_f32 v16, v160, v161
	v_cvt_pk_bf16_f32 v17, v162, v163
	v_cvt_pk_bf16_f32 v18, v164, v165
	v_cvt_pk_bf16_f32 v20, v168, v169
	v_cvt_pk_bf16_f32 v19, v166, v167
	v_cvt_pk_bf16_f32 v21, v170, v171
	v_cvt_pk_bf16_f32 v22, v172, v173
	v_cvt_pk_bf16_f32 v23, v174, v175
	v_cvt_pk_bf16_f32 v24, v176, v177
	v_cvt_pk_bf16_f32 v25, v178, v179
	v_cvt_pk_bf16_f32 v26, v180, v181
	v_cvt_pk_bf16_f32 v27, v182, v183
	v_cvt_pk_bf16_f32 v28, v184, v185
	v_cvt_pk_bf16_f32 v29, v186, v187
	v_cvt_pk_bf16_f32 v30, v188, v189
	v_cvt_pk_bf16_f32 v31, v190, v191
	v_or_b32_e32 v34, s0, v44
	v_ashrrev_i32_e32 v35, 31, v34
	s_waitcnt lgkmcnt(1)
	v_readfirstlane_b32 s1, v43
	v_readfirstlane_b32 s0, v42
	v_lshlrev_b64 v[34:35], 2, v[34:35]
	s_nop 0
	v_lshl_add_u64 v[42:43], s[0:1], 0, v[34:35]
	s_waitcnt lgkmcnt(0)
	v_readfirstlane_b32 s1, v39
	v_readfirstlane_b32 s0, v38
	global_load_dword v54, v[42:43], off
	s_nop 0
	v_lshl_add_u64 v[50:51], s[0:1], 0, v[34:35]
	v_readfirstlane_b32 s1, v41
	v_readfirstlane_b32 s0, v40
	global_load_dword v55, v[50:51], off
	s_nop 0
	v_lshl_add_u64 v[34:35], s[0:1], 0, v[34:35]
	global_load_dword v38, v[34:35], off
	global_load_dword v56, v[42:43], off offset:64
	global_load_dword v57, v[50:51], off offset:64
	s_nop 0
	global_load_dword v35, v[34:35], off offset:64
	v_mov_b32_e32 v34, 0
	s_cbranch_scc1 .LBB0_466
	s_add_i32 s0, s23, -3
	v_mad_i64_i32 v[40:41], s[0:1], s0, v244, v[36:37]
	global_load_ushort v39, v[40:41], off offset:3072
	s_add_i32 s0, s23, -2
	v_mad_i64_i32 v[40:41], s[0:1], s0, v244, v[36:37]
	s_add_i32 s0, s23, -1
	s_nop 0
	v_mad_i64_i32 v[42:43], s[0:1], s0, v244, v[36:37]
	s_waitcnt vmcnt(0)
	v_lshlrev_b32_e32 v58, 16, v39
	global_load_ushort v39, v[40:41], off offset:3072
	s_nop 0
	global_load_ushort v40, v[42:43], off offset:3072
	s_waitcnt vmcnt(1)
	v_lshlrev_b32_e32 v60, 16, v39
	s_waitcnt vmcnt(0)
	v_lshlrev_b32_e32 v59, 16, v40
